# v120: hoist 2 MFMAs above exp fmamk at L10124 and defer v_mov after lgkmcnt at L17204 (reschedule only)
# baseline (speedup 1.0000x reference)
.LBB0_405:
	v_add_u32_e32 v97, 0, v135
	v_add_u32_e32 v76, 0x10c00, v97
	ds_read_b128 v[76:79], v76
	v_add_u32_e32 v144, 0x10c40, v97
	ds_read_b128 v[144:147], v144
	v_add_u32_e32 v228, 0x10c80, v97
	ds_read_b128 v[228:231], v228
	v_add_u32_e32 v232, 0x10cc0, v97
	ds_read_b128 v[232:235], v232
	s_add_i32 s4, s4, -1
	v_add_u32_e32 v135, 0x1100, v135
	s_cmp_eq_u32 s4, 0
	s_waitcnt lgkmcnt(3)
	v_mfma_f32_16x16x32_bf16 v[80:83], v[76:79], v[0:3], 0
	v_mfma_f32_16x16x32_bf16 v[136:139], v[76:79], v[16:19], 0
	v_mfma_f32_16x16x32_bf16 v[140:143], v[76:79], v[32:35], 0
	v_mfma_f32_16x16x32_bf16 v[76:79], v[76:79], v[48:51], 0
	s_waitcnt lgkmcnt(2)
	v_mfma_f32_16x16x32_bf16 v[80:83], v[144:147], v[4:7], v[80:83]
	v_mfma_f32_16x16x32_bf16 v[136:139], v[144:147], v[20:23], v[136:139]
	v_mfma_f32_16x16x32_bf16 v[140:143], v[144:147], v[36:39], v[140:143]
	v_mfma_f32_16x16x32_bf16 v[76:79], v[144:147], v[52:55], v[76:79]
	s_waitcnt lgkmcnt(1)
	v_mfma_f32_16x16x32_bf16 v[80:83], v[228:231], v[8:11], v[80:83]
	v_mfma_f32_16x16x32_bf16 v[136:139], v[228:231], v[24:27], v[136:139]
	v_mfma_f32_16x16x32_bf16 v[140:143], v[228:231], v[40:43], v[140:143]
	v_mfma_f32_16x16x32_bf16 v[76:79], v[228:231], v[56:59], v[76:79]
	s_waitcnt lgkmcnt(0)
	v_mfma_f32_16x16x32_bf16 v[148:151], v[232:235], v[12:15], v[80:83]
	v_mfma_f32_16x16x32_bf16 v[80:83], v[232:235], v[28:31], v[136:139]
	v_mfma_f32_16x16x32_bf16 v[136:139], v[232:235], v[44:47], v[140:143]
	v_mfma_f32_16x16x32_bf16 v[76:79], v[232:235], v[60:63], v[76:79]
	s_nop 4
	v_fmamk_f32 v97, v148, 0xbfb8aa3b, v125
	s_nop 0
	v_exp_f32_e32 v97, v97
	s_nop 0
	v_add_f32_e32 v97, 1.0, v97
	v_rcp_f32_e32 v97, v97
	s_nop 0
	v_fmamk_f32 v143, v149, 0xbfb8aa3b, v125
	s_nop 0
	v_exp_f32_e32 v143, v143
	s_nop 1
	v_fmamk_f32 v137, v137, 0xbfb8aa3b, v126
	s_nop 0
	v_exp_f32_e32 v137, v137
	v_add_f32_e32 v143, 1.0, v143
	v_rcp_f32_e32 v143, v143
	v_add_f32_e32 v137, 1.0, v137
	v_rcp_f32_e32 v137, v137
	v_mul_f32_e32 v143, v143, v127
	v_exp_f32_e32 v143, v143
	v_fmamk_f32 v136, v136, 0xbfb8aa3b, v126
	v_exp_f32_e32 v136, v136
	v_fma_f32 v144, -v143, v143, 1.0
	v_max_f32_e32 v144, 0, v144
	v_sqrt_f32_e32 v144, v144
	v_mul_f32_e32 v97, v97, v127
	v_add_f32_e32 v136, 1.0, v136
	v_mul_f32_e32 v144, v137, v144
	v_fmamk_f32 v137, v150, 0xbfb8aa3b, v125
	v_exp_f32_e32 v137, v137
	v_fmamk_f32 v138, v138, 0xbfb8aa3b, v126
	v_rcp_f32_e32 v140, v136
	v_exp_f32_e32 v136, v97
	v_add_f32_e32 v137, 1.0, v137
	v_rcp_f32_e32 v137, v137
	v_exp_f32_e32 v138, v138
	v_fma_f32 v97, -v136, v136, 1.0
	v_mul_f32_e32 v137, v137, v127
	v_exp_f32_e32 v149, v137
	v_max_f32_e32 v97, 0, v97
	v_add_f32_e32 v138, 1.0, v138
	v_sqrt_f32_e32 v97, v97
	v_fma_f32 v137, -v149, v149, 1.0
	v_max_f32_e32 v137, 0, v137
	v_rcp_f32_e32 v138, v138
	v_sqrt_f32_e32 v137, v137
	v_add_u32_e32 v142, 0, v134
	v_mul_f32_e32 v97, v140, v97
	ds_read2_b32 v[140:141], v142 offset1:16
	ds_read2_b32 v[146:147], v142 offset0:132 offset1:148
	v_mul_f32_e32 v138, v138, v137
	v_add_u32_e32 v137, 0x400, v142
	v_fmamk_f32 v142, v151, 0xbfb8aa3b, v125
	v_exp_f32_e32 v142, v142
	v_fmamk_f32 v139, v139, 0xbfb8aa3b, v126
	v_exp_f32_e32 v139, v139
	v_add_f32_e32 v142, 1.0, v142
	v_rcp_f32_e32 v142, v142
	v_fmamk_f32 v80, v80, 0xbfb8aa3b, v130
	v_exp_f32_e32 v80, v80
	v_mul_f32_e32 v142, v142, v127
	v_exp_f32_e32 v151, v142
	v_add_f32_e32 v139, 1.0, v139
	v_rcp_f32_e32 v139, v139
	ds_read2_b32 v[152:153], v137 offset0:8 offset1:24
	v_fma_f32 v142, -v151, v151, 1.0
	v_max_f32_e32 v142, 0, v142
	v_sqrt_f32_e32 v142, v142
	ds_read2_b32 v[156:157], v137 offset0:140 offset1:156
	s_waitcnt lgkmcnt(3)
	v_mov_b32_e32 v137, v140
	v_mul_f32_e32 v140, 0, v136
	v_add_f32_e32 v80, 1.0, v80
	v_pk_fma_f32 v[158:159], v[136:137], v[96:97], v[140:141] op_sel_hi:[1,1,0]
	v_rcp_f32_e32 v80, v80
	v_mul_f32_e32 v154, v139, v142
	s_waitcnt lgkmcnt(2)
	v_mov_b32_e32 v142, v146
	v_mov_b32_e32 v145, v159
	v_mul_f32_e32 v140, v146, v144
	v_pk_fma_f32 v[144:145], v[142:143], v[144:145], v[140:141] op_sel_hi:[1,1,0]
	v_mul_f32_e32 v97, v136, v143
	s_waitcnt lgkmcnt(1)
	v_mov_b32_e32 v148, v152
	v_mov_b32_e32 v139, v145
	v_mul_f32_e32 v136, v152, v138
	v_pk_fma_f32 v[136:137], v[148:149], v[138:139], v[136:137] op_sel_hi:[1,1,0]
	v_mul_f32_e32 v80, v80, v128
	s_waitcnt lgkmcnt(0)
	v_mov_b32_e32 v150, v156
	v_mov_b32_e32 v155, v137
	v_mul_f32_e32 v136, v151, v137
	v_fmamk_f32 v76, v76, 0xbfb8aa3b, v129
	v_pk_fma_f32 v[136:137], v[150:151], v[154:155], v[136:137] op_sel_hi:[1,1,0]
	v_exp_f32_e32 v154, v80
	v_exp_f32_e32 v76, v76
	v_fmamk_f32 v77, v77, 0xbfb8aa3b, v129
	v_fma_f32 v80, -v154, v154, 1.0
	v_add_f32_e32 v76, 1.0, v76
	v_max_f32_e32 v80, 0, v80
	v_rcp_f32_e32 v76, v76
	v_sqrt_f32_e32 v80, v80
	v_exp_f32_e32 v77, v77
	v_fmamk_f32 v78, v78, 0xbfb8aa3b, v129
	v_mul_f32_e32 v155, v76, v80
	v_fmamk_f32 v76, v81, 0xbfb8aa3b, v130
	v_exp_f32_e32 v76, v76
	v_add_f32_e32 v77, 1.0, v77
	v_rcp_f32_e32 v80, v77
	v_exp_f32_e32 v78, v78
	v_add_f32_e32 v76, 1.0, v76
	v_rcp_f32_e32 v76, v76
	v_fmamk_f32 v79, v79, 0xbfb8aa3b, v129
	v_add_f32_e32 v78, 1.0, v78
	v_rcp_f32_e32 v78, v78
	v_mul_f32_e32 v76, v76, v128
	v_exp_f32_e32 v77, v76
	v_exp_f32_e32 v79, v79
	v_mul_f32_e32 v97, v149, v97
	v_fma_f32 v76, -v77, v77, 1.0
	v_max_f32_e32 v76, 0, v76
	v_sqrt_f32_e32 v76, v76
	v_add_f32_e32 v79, 1.0, v79
	v_rcp_f32_e32 v79, v79
	v_mul_f32_e32 v97, v151, v97
	v_mul_f32_e32 v80, v80, v76
	v_fmamk_f32 v76, v82, 0xbfb8aa3b, v130
	v_exp_f32_e32 v76, v76
	ds_bpermute_b32 v138, v93, v97
	ds_bpermute_b32 v142, v133, v97
	ds_bpermute_b32 v146, v131, v97
	v_add_f32_e32 v76, 1.0, v76
	v_rcp_f32_e32 v76, v76
	ds_bpermute_b32 v150, v132, v97
	v_mov_b32_e32 v97, v141
	v_mul_f32_e32 v82, v80, v147
	v_mul_f32_e32 v76, v76, v128
	v_exp_f32_e32 v159, v76
	v_mov_b32_e32 v158, v153
	ds_bpermute_b32 v140, v93, v136
	ds_bpermute_b32 v144, v133, v136
	v_fma_f32 v76, -v159, v159, 1.0
	v_max_f32_e32 v76, 0, v76
	v_sqrt_f32_e32 v76, v76
	ds_bpermute_b32 v148, v131, v136
	ds_bpermute_b32 v136, v132, v136
	v_add_u32_e32 v134, 0x2100, v134
	v_mul_f32_e32 v78, v78, v76
	v_fmamk_f32 v76, v83, 0xbfb8aa3b, v130
	s_nop 0
	v_exp_f32_e32 v76, v76
	s_nop 0
	v_add_f32_e32 v76, 1.0, v76
	v_rcp_f32_e32 v76, v76
	s_nop 0
	v_mul_f32_e32 v76, v76, v128
	s_nop 0
	v_exp_f32_e32 v83, v76
	s_nop 0
	v_fma_f32 v76, -v83, v83, 1.0
	v_max_f32_e32 v76, 0, v76
	v_sqrt_f32_e32 v76, v76
	s_nop 0
	v_mul_f32_e32 v152, v79, v76
	v_mul_f32_e32 v76, 0, v154
	v_pk_fma_f32 v[160:161], v[154:155], v[96:97], v[76:77] op_sel_hi:[1,1,0]
	v_mov_b32_e32 v76, v147
	v_mov_b32_e32 v81, v161
	v_pk_fma_f32 v[80:81], v[80:81], v[76:77], v[82:83] op_sel_hi:[1,1,0]
	v_mul_f32_e32 v76, v78, v153
	v_mov_b32_e32 v79, v81
	v_mul_f32_e32 v80, v154, v77
	v_pk_fma_f32 v[76:77], v[78:79], v[158:159], v[76:77] op_sel_hi:[1,1,0]
	v_mov_b32_e32 v82, v157
	v_mov_b32_e32 v153, v77
	v_mul_f32_e32 v76, v77, v83
	v_mul_f32_e32 v78, v159, v80
	v_pk_fma_f32 v[76:77], v[152:153], v[82:83], v[76:77] op_sel_hi:[1,1,0]
	ds_bpermute_b32 v141, v93, v76
	v_mul_f32_e32 v77, v83, v78
	ds_bpermute_b32 v139, v93, v77
	ds_bpermute_b32 v143, v133, v77
	ds_bpermute_b32 v145, v133, v76
	ds_bpermute_b32 v147, v131, v77
	ds_bpermute_b32 v149, v131, v76
	ds_bpermute_b32 v151, v132, v77
	ds_bpermute_b32 v137, v132, v76
	s_waitcnt lgkmcnt(6)
	v_pk_fma_f32 v[76:77], v[110:111], v[138:139], v[140:141]
	s_waitcnt lgkmcnt(4)
	v_pk_fma_f32 v[76:77], v[76:77], v[142:143], v[144:145]
	s_waitcnt lgkmcnt(2)
	v_pk_fma_f32 v[76:77], v[76:77], v[146:147], v[148:149]
	s_waitcnt lgkmcnt(0)
	v_pk_fma_f32 v[110:111], v[76:77], v[150:151], v[136:137]
	v_pk_mul_f32 v[76:77], v[138:139], v[142:143]
	s_nop 0
	v_pk_mul_f32 v[76:77], v[76:77], v[146:147]
	s_nop 0
	v_pk_mul_f32 v[76:77], v[76:77], v[150:151]
	s_nop 0
	v_pk_mul_f32 v[108:109], v[108:109], v[76:77]
	s_cbranch_scc0 .LBB0_405
